# E29: prompt-FoX tile loop anti-phase: waves 4-7 take their per-tile barrier (plus K/V stage-in and prefetch) between softmax-first-half and P.V, V triple-buffered in LDS; on E27
# baseline (speedup 1.0000x reference)
.LBB0_1338:
	s_lshl_b64 s[16:17], s[60:61], 10
	s_mov_b64 s[14:15], src_shared_base
	s_add_u32 s6, s59, s16
	s_addc_u32 s14, s50, s17
	s_lshl_b64 s[96:97], s[18:19], 1
	s_add_u32 s94, s6, s96
	s_getreg_b32 s6, hwreg(HW_REG_HW_ID, 0, 6)
	s_addc_u32 s95, s14, s97
	s_and_b32 s6, s6, 63
	s_lshl_b32 s6, s6, 2
	s_add_i32 s6, s6, 0
	s_add_i32 s6, s6, 0x23e00
	v_mov_b32_e32 v4, s6
	v_mov_b32_e32 v5, s15
	flat_load_dword v172, v[4:5] sc0 sc1
	s_waitcnt vmcnt(0)
	s_add_i32 s6, s12, -1
	s_cmpk_gt_i32 s13, 0x1ff
	s_mov_b64 s[18:19], -1
	s_cbranch_scc1 .LBB0_1403
	s_waitcnt lgkmcnt(0)
	v_readfirstlane_b32 s13, v172
	s_lshr_b32 s98, s13, 2
	v_mov_b32_e32 v153, v3
	s_mov_b64 s[14:15], src_shared_base
	v_lshl_add_u32 v2, s13, 6, v217
	v_mov_b32_e32 v19, 0
	v_readfirstlane_b32 s13, v2
	s_ashr_i32 s13, s13, 1
	s_andn2_b32 s13, s13, 31
	v_or_b32_e32 v146, s13, v212
	v_min_i32_e32 v4, s6, v146
	v_ashrrev_i32_e32 v5, 31, v4
	v_lshlrev_b64 v[4:5], 10, v[4:5]
	v_lshl_add_u64 v[4:5], s[94:95], 0, v[4:5]
	v_lshl_add_u64 v[4:5], v[4:5], 0, v[152:153]
	global_load_dwordx4 v[114:117], v[4:5], off
	global_load_dwordx4 v[118:121], v[4:5], off offset:32
	global_load_dwordx4 v[122:125], v[4:5], off offset:64
	global_load_dwordx4 v[126:129], v[4:5], off offset:96
	v_ashrrev_i32_e32 v4, 31, v2
	v_lshrrev_b32_e32 v4, 29, v4
	v_add_u32_e32 v5, v2, v4
	v_ashrrev_i32_e32 v4, 3, v5
	v_and_b32_e32 v5, -8, v5
	v_sub_u32_e32 v8, v2, v5
	v_ashrrev_i32_e32 v5, 31, v4
	v_lshlrev_b32_e32 v148, 3, v8
	v_lshlrev_b64 v[6:7], 9, v[4:5]
	v_ashrrev_i32_e32 v149, 31, v148
	v_lshl_add_u64 v[6:7], v[6:7], 0, v[148:149]
	v_lshlrev_b64 v[6:7], 1, v[6:7]
	v_lshl_add_u64 v[10:11], s[64:65], 0, v[6:7]
	v_lshl_add_u64 v[6:7], s[66:67], 0, v[6:7]
	v_add_u32_e32 v5, 0x200, v2
	global_load_dwordx4 v[134:137], v[6:7], off
	v_ashrrev_i32_e32 v6, 31, v5
	v_lshrrev_b32_e32 v6, 29, v6
	v_add_u32_e32 v7, v5, v6
	v_ashrrev_i32_e32 v6, 3, v7
	v_and_b32_e32 v7, -8, v7
	v_sub_u32_e32 v5, v5, v7
	v_ashrrev_i32_e32 v7, 31, v6
	v_lshlrev_b32_e32 v156, 3, v5
	global_load_dwordx4 v[130:133], v[10:11], off
	v_lshlrev_b64 v[10:11], 9, v[6:7]
	v_ashrrev_i32_e32 v157, 31, v156
	v_lshl_add_u64 v[10:11], v[10:11], 0, v[156:157]
	v_lshlrev_b64 v[10:11], 1, v[10:11]
	v_lshl_add_u64 v[12:13], s[64:65], 0, v[10:11]
	v_lshl_add_u64 v[10:11], s[66:67], 0, v[10:11]
	global_load_dwordx4 v[138:141], v[12:13], off
	global_load_dwordx4 v[142:145], v[10:11], off
	s_getreg_b32 s14, hwreg(HW_REG_HW_ID, 0, 6)
	s_and_b32 s14, s14, 63
	s_lshl_b32 s14, s14, 2
	s_add_i32 s14, s14, 0
	s_add_i32 s14, s14, 0x23e00
	v_mov_b32_e32 v10, s14
	v_mov_b32_e32 v11, s15
	flat_load_dword v7, v[10:11] sc0 sc1
	s_waitcnt vmcnt(0)
	v_mov_b32_e32 v10, 0
	s_waitcnt lgkmcnt(0)
	v_readfirstlane_b32 s14, v7
	s_nop 1
	v_lshl_add_u32 v13, s14, 6, v217
	v_lshl_add_u32 v7, v13, 3, v13
	v_cmp_gt_i32_e32 vcc, s9, v7
	s_and_saveexec_b64 s[20:21], vcc
	s_cbranch_execz .LBB0_1341
	v_mov_b32_e32 v9, s93
	v_mov_b32_e32 v10, s79
	v_cmp_gt_i32_e64 s[18:19], s11, v7
	v_subrev_u32_e32 v12, s11, v7
	s_nop 0
	v_cndmask_b32_e64 v11, v9, v10, s[18:19]
	v_mov_b32_e32 v9, s92
	v_mov_b32_e32 v10, s78
	v_cndmask_b32_e64 v10, v9, v10, s[18:19]
	v_ashrrev_i32_e32 v9, 31, v7
	v_cndmask_b32_e64 v15, 0, v9, s[18:19]
	v_cndmask_b32_e64 v14, v12, v7, s[18:19]
	v_lshlrev_b64 v[14:15], 5, v[14:15]
	v_lshl_add_u64 v[10:11], v[10:11], 0, v[14:15]
	global_load_dword v9, v[10:11], off
	s_waitcnt vmcnt(0)
	v_add_f32_e32 v10, 0, v9

.LBB0_1387:
	s_or_b64 exec, exec, s[18:19]
	s_movk_i32 s15, 0x90
	v_mul_lo_u32 v147, v4, s15
	v_lshlrev_b32_e32 v153, 4, v8
	v_add3_u32 v8, 0, v147, v153
	s_waitcnt lgkmcnt(0)
	s_barrier
	s_barrier
	ds_write_b128 v8, v[130:133]
	v_mad_u64_u32 v[8:9], s[16:17], v4, 48, v[8:9]
	v_mul_lo_u32 v174, v6, s15
	v_lshlrev_b32_e32 v175, 4, v5
	ds_write_b128 v8, v[134:137] offset:18432
	v_add3_u32 v8, 0, v174, v175
	v_lshrrev_b32_e32 v2, 2, v2
	s_cmp_lt_i32 s13, s12
	s_movk_i32 s18, 0xc0
	ds_write_b128 v8, v[138:141]
	v_mad_u64_u32 v[8:9], s[16:17], v6, 48, v[8:9]
	v_and_or_b32 v5, v2, 3, v216
	v_and_or_b32 v2, v2, 4, v225
	v_mov_b32_e32 v16, v3
	v_mov_b32_e32 v17, v3
	s_cselect_b64 s[84:85], -1, 0
	s_add_i32 s14, s9, 0x7f
	s_add_i32 s13, s13, s8
	v_mul_lo_u32 v173, v4, s18
	v_mul_lo_u32 v191, v6, s18
	ds_write_b128 v8, v[142:145] offset:18432
	v_lshlrev_b32_e32 v193, 3, v2
	v_mul_u32_u24_e32 v194, 0xc0, v5
	v_add_u32_e32 v196, 0x80, v6
	v_add_u32_e32 v197, 0x80, v4
	v_mov_b32_e32 v2, v3
	v_mov_b32_e32 v4, v3
	v_mov_b32_e32 v5, v3
	v_mov_b32_e32 v6, v3
	v_mov_b32_e32 v7, v3
	v_mov_b32_e32 v8, v3
	v_mov_b32_e32 v9, v3
	v_mov_b32_e32 v10, v3
	v_mov_b32_e32 v11, v3
	v_mov_b32_e32 v12, v3
	v_mov_b32_e32 v13, v3
	v_mov_b32_e32 v14, v3
	v_mov_b32_e32 v15, v3
	v_mov_b64_e32 v[32:33], v[16:17]
	v_mov_b64_e32 v[48:49], v[16:17]
	s_lshr_b32 s14, s14, 7
	s_movk_i32 s72, 0x90
	s_movk_i32 s73, 0xc0
	s_add_i32 s15, s13, 31
	v_add_u32_e32 v195, s13, v188
	s_mov_b32 s16, 0
	v_mov_b32_e32 v158, 0xf149f2ca
	v_mov_b32_e32 v192, 0
	v_mov_b32_e32 v198, v187
	v_mov_b64_e32 v[30:31], v[14:15]
	v_mov_b64_e32 v[28:29], v[12:13]
	v_mov_b64_e32 v[26:27], v[10:11]
	v_mov_b64_e32 v[24:25], v[8:9]
	v_mov_b64_e32 v[22:23], v[6:7]
	v_mov_b64_e32 v[20:21], v[4:5]
	v_mov_b64_e32 v[18:19], v[2:3]
	v_mov_b64_e32 v[46:47], v[14:15]
	v_mov_b64_e32 v[44:45], v[12:13]
	v_mov_b64_e32 v[42:43], v[10:11]
	v_mov_b64_e32 v[40:41], v[8:9]
	v_mov_b64_e32 v[38:39], v[6:7]
	v_mov_b64_e32 v[36:37], v[4:5]
	v_mov_b64_e32 v[34:35], v[2:3]
	s_mov_b32 s99, 0
	s_mov_b32 s100, 0xa800
	s_mov_b32 s101, 0x15800
	s_mov_b32 s18, 0
	s_waitcnt lgkmcnt(0)
	s_barrier
.LBB0_1388:
	s_add_i32 s17, s18, 1
	s_cmp_lt_u32 s17, s14
	s_cselect_b64 s[90:91], -1, 0
	s_cmp_ge_u32 s17, s14
	s_cbranch_scc1 .LBB0_1390
	s_cmp_eq_u32 s98, 0
	s_cbranch_scc1 .Lfx_doG
	s_cmp_lg_u32 s18, 0
	s_cbranch_scc1 .LBB0_1390
.Lfx_doG:
	v_add_u32_e32 v4, s16, v197
	v_ashrrev_i32_e32 v5, 31, v4
	v_lshlrev_b64 v[4:5], 9, v[4:5]
	v_lshl_add_u64 v[4:5], v[4:5], 0, v[148:149]
	v_lshlrev_b64 v[4:5], 1, v[4:5]
	v_lshl_add_u64 v[6:7], s[64:65], 0, v[4:5]
	v_lshl_add_u64 v[4:5], s[66:67], 0, v[4:5]
	global_load_dwordx4 v[134:137], v[4:5], off
	v_add_u32_e32 v4, s16, v196
	v_ashrrev_i32_e32 v5, 31, v4
	v_lshlrev_b64 v[4:5], 9, v[4:5]
	v_lshl_add_u64 v[4:5], v[4:5], 0, v[156:157]
	v_lshlrev_b64 v[4:5], 1, v[4:5]
	global_load_dwordx4 v[130:133], v[6:7], off
	v_lshl_add_u64 v[6:7], s[64:65], 0, v[4:5]
	v_lshl_add_u64 v[4:5], s[66:67], 0, v[4:5]
	global_load_dwordx4 v[138:141], v[6:7], off
	global_load_dwordx4 v[142:145], v[4:5], off

.LBB0_1395:
	v_pk_add_f32 v[10:11], v[86:87], v[158:159] op_sel_hi:[1,0] neg_lo:[0,1] neg_hi:[0,1]
	v_pk_add_f32 v[4:5], v[82:83], v[158:159] op_sel_hi:[1,0] neg_lo:[0,1] neg_hi:[0,1]
	v_exp_f32_e32 v168, v10
	v_exp_f32_e32 v169, v11
	v_pk_add_f32 v[10:11], v[88:89], v[158:159] op_sel_hi:[1,0] neg_lo:[0,1] neg_hi:[0,1]
	v_pk_add_f32 v[6:7], v[84:85], v[158:159] op_sel_hi:[1,0] neg_lo:[0,1] neg_hi:[0,1]
	v_exp_f32_e32 v170, v10
	v_exp_f32_e32 v171, v11
	v_pk_add_f32 v[10:11], v[90:91], v[158:159] op_sel_hi:[1,0] neg_lo:[0,1] neg_hi:[0,1]
	v_exp_f32_e32 v4, v4
	v_exp_f32_e32 v160, v10
	v_exp_f32_e32 v161, v11
	v_pk_add_f32 v[10:11], v[92:93], v[158:159] op_sel_hi:[1,0] neg_lo:[0,1] neg_hi:[0,1]
	v_exp_f32_e32 v5, v5
	v_exp_f32_e32 v162, v10
	v_exp_f32_e32 v163, v11
	v_pk_add_f32 v[10:11], v[94:95], v[158:159] op_sel_hi:[1,0] neg_lo:[0,1] neg_hi:[0,1]
	v_add3_u32 v2, s99, v193, v194
	v_exp_f32_e32 v164, v10
	v_exp_f32_e32 v165, v11
	v_pk_add_f32 v[10:11], v[96:97], v[158:159] op_sel_hi:[1,0] neg_lo:[0,1] neg_hi:[0,1]
	v_exp_f32_e32 v6, v6
	v_exp_f32_e32 v166, v10
	v_exp_f32_e32 v167, v11
	v_pk_add_f32 v[10:11], v[50:51], v[158:159] op_sel_hi:[1,0] neg_lo:[0,1] neg_hi:[0,1]
	v_exp_f32_e32 v7, v7
	v_exp_f32_e32 v90, v10
	v_exp_f32_e32 v91, v11
	v_pk_add_f32 v[10:11], v[52:53], v[158:159] op_sel_hi:[1,0] neg_lo:[0,1] neg_hi:[0,1]
	v_pk_add_f32 v[8:9], v[4:5], 0 op_sel_hi:[1,0]
	v_exp_f32_e32 v92, v10
	v_exp_f32_e32 v93, v11
	v_pk_add_f32 v[10:11], v[54:55], v[158:159] op_sel_hi:[1,0] neg_lo:[0,1] neg_hi:[0,1]
	v_pk_add_f32 v[8:9], v[6:7], v[8:9]
	v_exp_f32_e32 v94, v10
	v_exp_f32_e32 v95, v11
	v_pk_add_f32 v[10:11], v[56:57], v[158:159] op_sel_hi:[1,0] neg_lo:[0,1] neg_hi:[0,1]
	v_cvt_pk_bf16_f32 v4, v4, v5
	v_exp_f32_e32 v96, v10
	v_exp_f32_e32 v97, v11
	v_pk_add_f32 v[10:11], v[58:59], v[158:159] op_sel_hi:[1,0] neg_lo:[0,1] neg_hi:[0,1]
	v_cvt_pk_bf16_f32 v5, v6, v7
	v_exp_f32_e32 v82, v10
	v_exp_f32_e32 v83, v11
	v_pk_add_f32 v[10:11], v[60:61], v[158:159] op_sel_hi:[1,0] neg_lo:[0,1] neg_hi:[0,1]
	v_cvt_pk_bf16_f32 v6, v168, v169
	v_exp_f32_e32 v84, v10
	v_exp_f32_e32 v85, v11
	v_pk_add_f32 v[10:11], v[62:63], v[158:159] op_sel_hi:[1,0] neg_lo:[0,1] neg_hi:[0,1]
	v_cvt_pk_bf16_f32 v7, v170, v171
	v_exp_f32_e32 v86, v10
	v_exp_f32_e32 v87, v11
	v_pk_add_f32 v[10:11], v[64:65], v[158:159] op_sel_hi:[1,0] neg_lo:[0,1] neg_hi:[0,1]
	v_pk_add_f32 v[8:9], v[168:169], v[8:9]
	v_exp_f32_e32 v88, v10
	v_exp_f32_e32 v89, v11
	v_pk_add_f32 v[10:11], v[66:67], v[158:159] op_sel_hi:[1,0] neg_lo:[0,1] neg_hi:[0,1]
	v_pk_add_f32 v[8:9], v[170:171], v[8:9]
	v_exp_f32_e32 v66, v10
	v_exp_f32_e32 v67, v11
	v_pk_add_f32 v[10:11], v[68:69], v[158:159] op_sel_hi:[1,0] neg_lo:[0,1] neg_hi:[0,1]
	v_pk_add_f32 v[8:9], v[160:161], v[8:9]
	v_exp_f32_e32 v68, v10
	v_exp_f32_e32 v69, v11
	v_pk_add_f32 v[10:11], v[70:71], v[158:159] op_sel_hi:[1,0] neg_lo:[0,1] neg_hi:[0,1]
	v_pk_add_f32 v[8:9], v[162:163], v[8:9]
	v_exp_f32_e32 v70, v10
	v_exp_f32_e32 v71, v11
	v_pk_add_f32 v[10:11], v[72:73], v[158:159] op_sel_hi:[1,0] neg_lo:[0,1] neg_hi:[0,1]
	v_pk_add_f32 v[8:9], v[164:165], v[8:9]
	v_exp_f32_e32 v72, v10
	v_exp_f32_e32 v73, v11
	v_pk_add_f32 v[10:11], v[74:75], v[158:159] op_sel_hi:[1,0] neg_lo:[0,1] neg_hi:[0,1]
	v_pk_add_f32 v[8:9], v[166:167], v[8:9]
	v_exp_f32_e32 v58, v10
	v_exp_f32_e32 v59, v11
	v_pk_add_f32 v[10:11], v[76:77], v[158:159] op_sel_hi:[1,0] neg_lo:[0,1] neg_hi:[0,1]
	s_cmp_eq_u32 s98, 0
	s_cbranch_scc1 .Lfx_p3
	s_cmp_eq_u64 s[90:91], 0
	s_cbranch_scc1 .LfxB_nolw1
	s_bitcmp1_b32 s17, 0
	s_cselect_b32 s18, 0xa800, 0
	v_add3_u32 v199, s18, v147, v153
	v_add3_u32 v200, s100, v173, v153
	v_add3_u32 v201, s18, v174, v175
	v_add3_u32 v202, s100, v191, v175
	s_waitcnt vmcnt(2)
	ds_write_b128 v199, v[130:133]
	ds_write_b128 v200, v[134:137] offset:18432
	s_waitcnt vmcnt(1)
	ds_write_b128 v201, v[138:141]
	s_waitcnt vmcnt(0)
	ds_write_b128 v202, v[142:145] offset:18432
.LfxB_nolw1:
	s_waitcnt lgkmcnt(0)
	s_barrier
	s_add_i32 s18, s17, 1
	s_cmp_ge_u32 s18, s14
	s_cbranch_scc1 .LfxB_nog1
	s_add_i32 s18, s16, 0x80
	v_add_u32_e32 v204, s18, v197
	v_ashrrev_i32_e32 v205, 31, v204
	v_lshlrev_b64 v[204:205], 9, v[204:205]
	v_lshl_add_u64 v[204:205], v[204:205], 0, v[148:149]
	v_lshlrev_b64 v[204:205], 1, v[204:205]
	v_lshl_add_u64 v[206:207], s[64:65], 0, v[204:205]
	v_lshl_add_u64 v[204:205], s[66:67], 0, v[204:205]
	global_load_dwordx4 v[134:137], v[204:205], off
	v_add_u32_e32 v204, s18, v196
	v_ashrrev_i32_e32 v205, 31, v204
	v_lshlrev_b64 v[204:205], 9, v[204:205]
	v_lshl_add_u64 v[204:205], v[204:205], 0, v[156:157]
	v_lshlrev_b64 v[204:205], 1, v[204:205]
	global_load_dwordx4 v[130:133], v[206:207], off
	v_lshl_add_u64 v[206:207], s[64:65], 0, v[204:205]
	v_lshl_add_u64 v[204:205], s[66:67], 0, v[204:205]
	global_load_dwordx4 v[138:141], v[206:207], off
	global_load_dwordx4 v[142:145], v[204:205], off
.LfxB_nog1:
.Lfx_p3:
	ds_read_b64_tr_b16 v[74:75], v2 offset:18432
	ds_read_b64_tr_b16 v[76:77], v2 offset:19968
	s_waitcnt lgkmcnt(0)
	v_mfma_f32_32x32x16_bf16 v[34:49], v[74:77], v[4:7], v[34:49]
	ds_read_b64_tr_b16 v[74:75], v2 offset:18496
	ds_read_b64_tr_b16 v[76:77], v2 offset:20032
	v_add_f32_e64 v8, v90, v8
	v_add_f32_e64 v9, v91, v9
	v_exp_f32_e32 v60, v10
	v_pk_add_f32 v[8:9], v[92:93], v[8:9]
	v_exp_f32_e32 v61, v11
	v_pk_add_f32 v[8:9], v[94:95], v[8:9]
	v_pk_add_f32 v[10:11], v[78:79], v[158:159] op_sel_hi:[1,0] neg_lo:[0,1] neg_hi:[0,1]
	s_waitcnt lgkmcnt(0)
	v_mfma_f32_32x32x16_bf16 v[18:33], v[74:77], v[4:7], v[18:33]
	ds_read_b64_tr_b16 v[74:75], v2 offset:21504
	ds_read_b64_tr_b16 v[76:77], v2 offset:23040
	v_cvt_pk_bf16_f32 v4, v160, v161
	v_cvt_pk_bf16_f32 v5, v162, v163
	v_cvt_pk_bf16_f32 v6, v164, v165
	v_cvt_pk_bf16_f32 v7, v166, v167
	v_pk_add_f32 v[8:9], v[96:97], v[8:9]
	v_exp_f32_e32 v62, v10
	s_waitcnt lgkmcnt(0)
	v_mfma_f32_32x32x16_bf16 v[34:49], v[74:77], v[4:7], v[34:49]
	ds_read_b64_tr_b16 v[74:75], v2 offset:21568
	ds_read_b64_tr_b16 v[76:77], v2 offset:23104
	v_add_f32_e64 v8, v82, v8
	v_add_f32_e64 v9, v83, v9
	v_exp_f32_e32 v63, v11
	v_pk_add_f32 v[8:9], v[84:85], v[8:9]
	v_pk_add_f32 v[10:11], v[80:81], v[158:159] op_sel_hi:[1,0] neg_lo:[0,1] neg_hi:[0,1]
	v_pk_add_f32 v[8:9], v[86:87], v[8:9]
	v_exp_f32_e32 v64, v10
	s_waitcnt lgkmcnt(0)
	v_mfma_f32_32x32x16_bf16 v[18:33], v[74:77], v[4:7], v[18:33]
	ds_read_b64_tr_b16 v[74:75], v2 offset:24576
	ds_read_b64_tr_b16 v[76:77], v2 offset:26112
	v_cvt_pk_bf16_f32 v4, v90, v91
	v_cvt_pk_bf16_f32 v5, v92, v93
	v_cvt_pk_bf16_f32 v6, v94, v95
	v_cvt_pk_bf16_f32 v7, v96, v97
	v_pk_add_f32 v[8:9], v[88:89], v[8:9]
	v_exp_f32_e32 v65, v11
	s_waitcnt lgkmcnt(0)
	v_mfma_f32_32x32x16_bf16 v[34:49], v[74:77], v[4:7], v[34:49]
	ds_read_b64_tr_b16 v[74:75], v2 offset:24640
	ds_read_b64_tr_b16 v[76:77], v2 offset:26176
	v_add_f32_e64 v8, v66, v8
	v_add_f32_e64 v9, v67, v9
	v_add_f32_e64 v10, v98, -v158
	v_add_f32_e64 v11, v99, -v158
	v_pk_add_f32 v[8:9], v[68:69], v[8:9]
	v_exp_f32_e32 v50, v10
	v_pk_add_f32 v[8:9], v[70:71], v[8:9]
	v_exp_f32_e32 v51, v11
	s_waitcnt lgkmcnt(0)
	v_mfma_f32_32x32x16_bf16 v[18:33], v[74:77], v[4:7], v[18:33]
	ds_read_b64_tr_b16 v[74:75], v2 offset:27648
	ds_read_b64_tr_b16 v[76:77], v2 offset:29184
	v_cvt_pk_bf16_f32 v4, v82, v83
	v_cvt_pk_bf16_f32 v5, v84, v85
	v_cvt_pk_bf16_f32 v6, v86, v87
	v_cvt_pk_bf16_f32 v7, v88, v89
	v_pk_add_f32 v[8:9], v[72:73], v[8:9]
	v_pk_add_f32 v[10:11], v[100:101], v[158:159] op_sel_hi:[1,0] neg_lo:[0,1] neg_hi:[0,1]
	s_waitcnt lgkmcnt(0)
	v_mfma_f32_32x32x16_bf16 v[34:49], v[74:77], v[4:7], v[34:49]
	ds_read_b64_tr_b16 v[74:75], v2 offset:27712
	ds_read_b64_tr_b16 v[76:77], v2 offset:29248
	v_add_f32_e64 v8, v58, v8
	v_add_f32_e64 v9, v59, v9
	v_exp_f32_e32 v52, v10
	v_pk_add_f32 v[8:9], v[60:61], v[8:9]
	v_exp_f32_e32 v53, v11
	v_pk_add_f32 v[8:9], v[62:63], v[8:9]
	v_pk_add_f32 v[10:11], v[102:103], v[158:159] op_sel_hi:[1,0] neg_lo:[0,1] neg_hi:[0,1]
	s_waitcnt lgkmcnt(0)
	v_mfma_f32_32x32x16_bf16 v[18:33], v[74:77], v[4:7], v[18:33]
	v_cvt_pk_bf16_f32 v4, v66, v67
	v_cvt_pk_bf16_f32 v5, v68, v69
	ds_read_b64_tr_b16 v[66:67], v2 offset:30720
	ds_read_b64_tr_b16 v[68:69], v2 offset:32256
	v_cvt_pk_bf16_f32 v6, v70, v71
	v_cvt_pk_bf16_f32 v7, v72, v73
	v_pk_add_f32 v[8:9], v[64:65], v[8:9]
	v_exp_f32_e32 v54, v10
	s_waitcnt lgkmcnt(0)
	v_mfma_f32_32x32x16_bf16 v[34:49], v[66:69], v[4:7], v[34:49]
	ds_read_b64_tr_b16 v[66:67], v2 offset:30784
	ds_read_b64_tr_b16 v[68:69], v2 offset:32320
	v_add_f32_e64 v8, v50, v8
	v_add_f32_e64 v9, v51, v9
	v_exp_f32_e32 v55, v11
	v_pk_add_f32 v[10:11], v[104:105], v[158:159] op_sel_hi:[1,0] neg_lo:[0,1] neg_hi:[0,1]
	v_pk_add_f32 v[8:9], v[52:53], v[8:9]
	v_exp_f32_e32 v56, v10
	v_exp_f32_e32 v57, v11
	s_waitcnt lgkmcnt(0)
	v_mfma_f32_32x32x16_bf16 v[18:33], v[66:69], v[4:7], v[18:33]
	v_cvt_pk_bf16_f32 v4, v58, v59
	v_cvt_pk_bf16_f32 v5, v60, v61
	ds_read_b64_tr_b16 v[58:59], v2 offset:33792
	ds_read_b64_tr_b16 v[60:61], v2 offset:35328
	v_cvt_pk_bf16_f32 v6, v62, v63
	v_cvt_pk_bf16_f32 v7, v64, v65
	v_pk_add_f32 v[10:11], v[106:107], v[158:159] op_sel_hi:[1,0] neg_lo:[0,1] neg_hi:[0,1]
	v_pk_add_f32 v[12:13], v[108:109], v[158:159] op_sel_hi:[1,0] neg_lo:[0,1] neg_hi:[0,1]
	s_waitcnt lgkmcnt(0)
	v_mfma_f32_32x32x16_bf16 v[34:49], v[58:61], v[4:7], v[34:49]
	ds_read_b64_tr_b16 v[58:59], v2 offset:33856
	ds_read_b64_tr_b16 v[60:61], v2 offset:35392
	v_exp_f32_e32 v10, v10
	v_exp_f32_e32 v11, v11
	v_exp_f32_e32 v12, v12
	v_exp_f32_e32 v13, v13
	v_pk_add_f32 v[8:9], v[54:55], v[8:9]
	v_pk_add_f32 v[14:15], v[110:111], v[158:159] op_sel_hi:[1,0] neg_lo:[0,1] neg_hi:[0,1]
	s_waitcnt lgkmcnt(0)
	v_mfma_f32_32x32x16_bf16 v[18:33], v[58:61], v[4:7], v[18:33]
	v_cvt_pk_bf16_f32 v4, v50, v51
	v_cvt_pk_bf16_f32 v5, v52, v53
	ds_read_b64_tr_b16 v[50:51], v2 offset:36864
	ds_read_b64_tr_b16 v[52:53], v2 offset:38400
	v_cvt_pk_bf16_f32 v6, v54, v55
	v_cvt_pk_bf16_f32 v7, v56, v57
	v_pk_add_f32 v[8:9], v[56:57], v[8:9]
	v_pk_add_f32 v[16:17], v[112:113], v[158:159] op_sel_hi:[1,0] neg_lo:[0,1] neg_hi:[0,1]
	s_waitcnt lgkmcnt(0)
	v_mfma_f32_32x32x16_bf16 v[34:49], v[50:53], v[4:7], v[34:49]
	ds_read_b64_tr_b16 v[50:51], v2 offset:36928
	ds_read_b64_tr_b16 v[52:53], v2 offset:38464
	v_add_f32_e64 v8, v10, v8
	v_add_f32_e64 v9, v11, v9
	v_exp_f32_e32 v14, v14
	v_pk_add_f32 v[8:9], v[12:13], v[8:9]
	v_exp_f32_e32 v15, v15
	v_exp_f32_e32 v16, v16
	v_exp_f32_e32 v17, v17
	s_waitcnt lgkmcnt(0)
	v_mfma_f32_32x32x16_bf16 v[18:33], v[50:53], v[4:7], v[18:33]
	v_cvt_pk_bf16_f32 v4, v10, v11
	v_cvt_pk_bf16_f32 v5, v12, v13
	ds_read_b64_tr_b16 v[10:11], v2 offset:39936
	ds_read_b64_tr_b16 v[12:13], v2 offset:41472
	v_cvt_pk_bf16_f32 v6, v14, v15
	v_cvt_pk_bf16_f32 v7, v16, v17
	v_pk_add_f32 v[8:9], v[14:15], v[8:9]
	s_waitcnt lgkmcnt(0)
	v_mfma_f32_32x32x16_bf16 v[34:49], v[10:13], v[4:7], v[34:49]
	ds_read_b64_tr_b16 v[10:11], v2 offset:40000
	ds_read_b64_tr_b16 v[12:13], v2 offset:41536
	v_add_f32_e64 v8, v16, v8
	v_add_f32_e64 v9, v17, v9
	v_add_f32_e32 v2, v8, v9
	v_add_f32_e32 v192, v192, v2
	s_waitcnt lgkmcnt(0)
	v_mfma_f32_32x32x16_bf16 v[18:33], v[10:13], v[4:7], v[18:33]
.LBB0_1396:
	s_cmp_lg_u32 s98, 0
	s_cbranch_scc1 .LBB0_1398
	s_andn2_b64 vcc, exec, s[90:91]
	s_cbranch_vccnz .LBB0_1398
	s_bitcmp1_b32 s17, 0
	s_cselect_b32 s18, 0xa800, 0
	s_add_i32 s18, s18, 0
	v_add3_u32 v6, s18, v147, v153
	v_add3_u32 v2, s100, v191, v175
	v_add3_u32 v4, s18, v174, v175
	v_add3_u32 v5, s100, v173, v153
	s_waitcnt vmcnt(2)
	ds_write_b128 v6, v[130:133]
	ds_write_b128 v5, v[134:137] offset:18432
	s_waitcnt vmcnt(1)
	ds_write_b128 v4, v[138:141]
	s_waitcnt vmcnt(0)
	ds_write_b128 v2, v[142:145] offset:18432
.LBB0_1398:
	s_addk_i32 s16, 0x80
	v_add_u32_e32 v198, 0x200, v198
	v_add_u32_e32 v195, 0xffffff80, v195
	s_mov_b32 s18, s99
	s_mov_b32 s99, s100
	s_mov_b32 s100, s101
	s_mov_b32 s101, s18
	s_cmp_lg_u32 s98, 0
	s_cbranch_scc1 .Lfx_nobar
	s_waitcnt lgkmcnt(0)
	s_barrier
.Lfx_nobar:
	s_cmp_eq_u32 s14, s17
	s_cbranch_scc1 .LBB0_1400
	s_mov_b32 s18, s17
	s_branch .LBB0_1388
.Lfx_skip:
	s_cmp_eq_u32 s98, 0
	s_cbranch_scc1 .LBB0_1396
	s_cmp_eq_u64 s[90:91], 0
	s_cbranch_scc1 .LfxB_nolw2
	s_bitcmp1_b32 s17, 0
	s_cselect_b32 s18, 0xa800, 0
	v_add3_u32 v199, s18, v147, v153
	v_add3_u32 v200, s100, v173, v153
	v_add3_u32 v201, s18, v174, v175
	v_add3_u32 v202, s100, v191, v175
	s_waitcnt vmcnt(2)
	ds_write_b128 v199, v[130:133]
	ds_write_b128 v200, v[134:137] offset:18432
	s_waitcnt vmcnt(1)
	ds_write_b128 v201, v[138:141]
	s_waitcnt vmcnt(0)
	ds_write_b128 v202, v[142:145] offset:18432

.LfxB_nog2:
	s_branch .LBB0_1396
.LBB0_1400:
	ds_bpermute_b32 v2, v177, v192
	v_cmp_gt_i32_e32 vcc, s12, v146
	s_and_saveexec_b64 s[14:15], vcc
	s_xor_b64 s[18:19], exec, s[14:15]
	s_cbranch_execz .LBB0_1402
	s_waitcnt lgkmcnt(0)
	v_add_f32_e32 v2, v192, v2
	v_div_scale_f32 v4, s[16:17], v2, v2, 1.0
	v_rcp_f32_e32 v5, v4
	s_lshl_b64 s[14:15], s[60:61], 11
	v_readlane_b32 s13, v244, 42
	s_add_u32 s13, s13, s14
	v_fma_f32 v6, -v4, v5, 1.0
	v_fmac_f32_e32 v5, v6, v5
	v_div_scale_f32 v6, vcc, 1.0, v2, 1.0
	v_mul_f32_e32 v7, v6, v5
	v_fma_f32 v8, -v4, v7, v6
	v_readlane_b32 s14, v244, 43
	v_fmac_f32_e32 v7, v8, v5
	s_addc_u32 s15, s14, s15
	v_fma_f32 v4, -v4, v7, v6
	s_add_u32 s14, s13, s96
	v_div_fmas_f32 v4, v4, v5, v7
	v_ashrrev_i32_e32 v147, 31, v146
	s_addc_u32 s15, s15, s97
	v_div_fixup_f32 v4, v4, v2, 1.0
	v_lshlrev_b64 v[6:7], 11, v[146:147]
	v_lshl_add_u64 v[6:7], s[14:15], 0, v[6:7]
	v_lshlrev_b32_e32 v2, 2, v216
	v_lshl_add_u64 v[6:7], v[6:7], 0, v[2:3]
	v_pk_mul_f32 v[60:61], v[34:35], v[4:5] op_sel_hi:[1,0]
	v_pk_mul_f32 v[62:63], v[36:37], v[4:5] op_sel_hi:[1,0]
	v_pk_mul_f32 v[64:65], v[38:39], v[4:5] op_sel_hi:[1,0]
	v_pk_mul_f32 v[66:67], v[40:41], v[4:5] op_sel_hi:[1,0]
	v_cvt_pk_bf16_f32 v8, v60, v61
	v_cvt_pk_bf16_f32 v9, v62, v63
	v_cvt_pk_bf16_f32 v10, v64, v65
	v_cvt_pk_bf16_f32 v11, v66, v67
	s_nop 1
	v_permlane32_swap_b32_e32 v8, v10
	v_permlane32_swap_b32_e32 v9, v11
	global_store_dwordx4 v[6:7], v[8:11], off
	v_pk_mul_f32 v[60:61], v[42:43], v[4:5] op_sel_hi:[1,0]
	v_pk_mul_f32 v[62:63], v[44:45], v[4:5] op_sel_hi:[1,0]
	v_pk_mul_f32 v[64:65], v[46:47], v[4:5] op_sel_hi:[1,0]
	v_pk_mul_f32 v[66:67], v[48:49], v[4:5] op_sel_hi:[1,0]
	v_cvt_pk_bf16_f32 v50, v60, v61
	v_cvt_pk_bf16_f32 v51, v62, v63
	v_cvt_pk_bf16_f32 v52, v64, v65
	v_cvt_pk_bf16_f32 v53, v66, v67
	s_nop 1
	v_permlane32_swap_b32_e32 v50, v52
	v_permlane32_swap_b32_e32 v51, v53
	global_store_dwordx4 v[6:7], v[50:53], off offset:32
	v_pk_mul_f32 v[60:61], v[18:19], v[4:5] op_sel_hi:[1,0]
	v_pk_mul_f32 v[62:63], v[20:21], v[4:5] op_sel_hi:[1,0]
	v_pk_mul_f32 v[64:65], v[22:23], v[4:5] op_sel_hi:[1,0]
	v_pk_mul_f32 v[66:67], v[24:25], v[4:5] op_sel_hi:[1,0]
	v_cvt_pk_bf16_f32 v8, v60, v61
	v_cvt_pk_bf16_f32 v9, v62, v63
	v_cvt_pk_bf16_f32 v10, v64, v65
	v_cvt_pk_bf16_f32 v11, v66, v67
	s_nop 1
	v_permlane32_swap_b32_e32 v8, v10
	v_permlane32_swap_b32_e32 v9, v11
	global_store_dwordx4 v[6:7], v[8:11], off offset:64
	v_pk_mul_f32 v[60:61], v[26:27], v[4:5] op_sel_hi:[1,0]
	v_pk_mul_f32 v[62:63], v[28:29], v[4:5] op_sel_hi:[1,0]
	v_pk_mul_f32 v[64:65], v[30:31], v[4:5] op_sel_hi:[1,0]
	v_pk_mul_f32 v[66:67], v[32:33], v[4:5] op_sel_hi:[1,0]
	v_cvt_pk_bf16_f32 v50, v60, v61
	v_cvt_pk_bf16_f32 v51, v62, v63
	v_cvt_pk_bf16_f32 v52, v64, v65
	v_cvt_pk_bf16_f32 v53, v66, v67
	s_nop 1
	v_permlane32_swap_b32_e32 v50, v52
	v_permlane32_swap_b32_e32 v51, v53
	global_store_dwordx4 v[6:7], v[50:53], off offset:96
